# W1 phase below the last layer: the four-tile CUs start ~12 us late, so that the panel-sharing CUs are no longer in lockstep
# speedup vs baseline: 1.0049x; 1.0010x over previous
; DI void phase_g5(const Frame& F) {
;     const unsigned char* W = F.ws + WS_W; const int nM = (F.l == NL - 1 ? ML : MT) / 256;
;     pg8::Sched2 S; S.tileBytes = 256L * 1024 * 2; S.G = F.G; S.c = F.bid;
;     S.j0 = pg8::JobD{(const char*)(F.ws + WS_HB), (const char*)(W + W_1), nM, 16, 1, 0, 0}; S.j1 = S.j0; S.n0 = nM * 16; S.total = S.n0;
;     EpiW1 E{F};
;     pg8::gemm_phase(F.lds, 1024, S, E, F.tid);
.LBB0_89:
	s_cmp_lt_u32 s96, 0x80
	s_cbranch_scc1 .Lg5_nodelay
	v_readlane_b32 s2, v255, 35
	s_cmp_eq_u32 s2, 3
	s_cbranch_scc1 .Lg5_nodelay
	s_sleep 127
	s_sleep 127
	s_sleep 127
